# in-proj epilogue: nt stores for the gate column tiles only (read once, late); q/k/v tiles keep the default policy
# speedup vs baseline: 1.0168x; 1.0168x over previous
; #define PG8_STAGE(bufoff, gbase, voff) do { _Pragma("unroll") for (int _i = 0; _i < 2; ++_i) \
;         __builtin_amdgcn_global_load_lds((const unsigned*)((const char*)(gbase) + (voff)[_i]), (LAS unsigned*)(lds + (bufoff) + ldsw + _i * 8192), 16, 0, 0); } while (0)
; #define PG8_LDA(dst, b, h) do { _Pragma("unroll") for (int m = 0; m < 4; ++m) _Pragma("unroll") for (int k = 0; k < 2; ++k) dst[m][k] = *(const LAS bf16x8*)(lds + PG8_SA(b, h) + aoff + m * 2048 + k * 1024); } while (0)
; #define PG8_LDB(dst, b, h) do { _Pragma("unroll") for (int n = 0; n < 2; ++n) _Pragma("unroll") for (int k = 0; k < 2; ++k) dst[n][k] = *(const LAS bf16x8*)(lds + PG8_SB(b, h) + boff + n * 2048 + k * 1024); } while (0)
; #define PG8_MMA(ai, bj, At, Bt) do { __builtin_amdgcn_s_setprio(1); _Pragma("unroll") for (int m = 0; m < 4; ++m) _Pragma("unroll") for (int n = 0; n < 2; ++n) _Pragma("unroll") for (int k = 0; k < 2; ++k) \
;         acc[ai][bj][m][n] = __builtin_amdgcn_mfma_f32_16x16x32_bf16(Bt[n][k], At[m][k], acc[ai][bj][m][n], 0, 0, 0); __builtin_amdgcn_s_setprio(0); } while (0)
; #define PG8_WAIT_V(n) asm volatile("s_waitcnt vmcnt(" #n ")" ::: "memory")
; #define PG8_WAIT_L(n) asm volatile("s_waitcnt lgkmcnt(" #n ")" ::: "memory")
; #define PG8_BAR __builtin_amdgcn_s_barrier()
; #define PG8_SCHED __builtin_amdgcn_sched_barrier(0)
; template <class Epi>
; DI void gemm_phase(LAS unsigned char* lds, const Gemm g, const StaticOrder& S, const Epi& E, const int tid) {
;     ...
;             PG8_LDB(B0, 0, 0); PG8_SCHED; PG8_LDA(At, 0, 0); PG8_STAGE(PG8_SA(1, 1), a1 + hstepA, voffA);
;             PG8_WAIT_L(8); PG8_BAR; PG8_WAIT_L(0); PG8_MMA(0, 0, At, B0); PG8_BAR; PG8_SCHED;
;             PG8_LDB(B1, 0, 1); PG8_STAGE(PG8_SB(0, 0), b2, voffB);
;             PG8_BAR; PG8_WAIT_L(0); PG8_MMA(0, 1, At, B1); PG8_BAR;
;             PG8_LDA(At, 0, 1); PG8_STAGE(PG8_SA(0, 0), a2, voffA);
;             PG8_BAR; PG8_WAIT_L(0); PG8_MMA(1, 0, At, B0); PG8_BAR; PG8_SCHED;
;             PG8_STAGE(PG8_SB(0, 1), b2 + hstepB, voffB);
;             PG8_WAIT_V(6); PG8_BAR; PG8_MMA(1, 1, At, B1); PG8_BAR;
.LBB0_62:
	s_add_i32 s69, 0, 0x10000
	ds_read_b128 v[158:161], v241
	ds_read_b128 v[162:165], v241 offset:1024
	ds_read_b128 v[166:169], v241 offset:2048
	ds_read_b128 v[178:181], v241 offset:3072
	s_add_i32 m0, s41, 0xc000
	ds_read_b128 v[182:185], v151
	ds_read_b128 v[186:189], v151 offset:1024
	ds_read_b128 v[190:193], v151 offset:2048
	ds_read_b128 v[194:197], v151 offset:3072
	ds_read_b128 v[198:201], v151 offset:4096
	ds_read_b128 v[202:205], v151 offset:5120
	ds_read_b128 v[206:209], v151 offset:6144
	ds_read_b128 v[210:213], v151 offset:7168
	global_load_lds_dwordx4 v138, s[86:87]
	s_add_i32 m0, s41, 0xe000
	s_nop 0
	global_load_lds_dwordx4 v140, s[86:87]
	s_waitcnt lgkmcnt(8)
	s_barrier
	s_waitcnt lgkmcnt(0)
	s_setprio 1
	s_waitcnt lgkmcnt(0)
	v_mfma_f32_16x16x32_bf16 v[126:129], v[158:161], v[182:185], v[126:129]
	v_mfma_f32_16x16x32_bf16 v[122:125], v[166:169], v[182:185], v[122:125]
	v_mfma_f32_16x16x32_bf16 v[118:121], v[158:161], v[190:193], v[118:121]
	v_mfma_f32_16x16x32_bf16 v[114:117], v[166:169], v[190:193], v[114:117]
	v_mfma_f32_16x16x32_bf16 v[102:105], v[158:161], v[198:201], v[102:105]
	v_mfma_f32_16x16x32_bf16 v[98:101], v[166:169], v[198:201], v[98:101]
	v_mfma_f32_16x16x32_bf16 v[86:89], v[158:161], v[206:209], v[86:89]
	v_mfma_f32_16x16x32_bf16 v[82:85], v[166:169], v[206:209], v[82:85]
	v_mfma_f32_16x16x32_bf16 v[126:129], v[162:165], v[186:189], v[126:129]
	v_mfma_f32_16x16x32_bf16 v[122:125], v[178:181], v[186:189], v[122:125]
	v_mfma_f32_16x16x32_bf16 v[118:121], v[162:165], v[194:197], v[118:121]
	v_mfma_f32_16x16x32_bf16 v[114:117], v[178:181], v[194:197], v[114:117]
	v_mfma_f32_16x16x32_bf16 v[102:105], v[162:165], v[202:205], v[102:105]
	v_mfma_f32_16x16x32_bf16 v[98:101], v[178:181], v[202:205], v[98:101]
	v_mfma_f32_16x16x32_bf16 v[86:89], v[162:165], v[210:213], v[86:89]
	v_mfma_f32_16x16x32_bf16 v[82:85], v[178:181], v[210:213], v[82:85]
	s_setprio 0
	s_barrier
	s_add_i32 s78, 0, 0x14000
	s_add_i32 s69, s69, s26
	ds_read_b128 v[214:217], v242
	ds_read_b128 v[218:221], v242 offset:1024
	ds_read_b128 v[222:225], v242 offset:2048
	ds_read_b128 v[226:229], v242 offset:3072
	s_mov_b32 m0, s69
	s_nop 0
	global_load_lds_dwordx4 v0, s[6:7]
	s_add_i32 m0, s69, 0x2000
	s_nop 0
	global_load_lds_dwordx4 v130, s[6:7]
	s_barrier
	s_waitcnt lgkmcnt(0)
	s_setprio 1
	s_waitcnt lgkmcnt(0)
	v_mfma_f32_16x16x32_bf16 v[110:113], v[214:217], v[182:185], v[110:113]
	v_mfma_f32_16x16x32_bf16 v[106:109], v[222:225], v[182:185], v[106:109]
	v_mfma_f32_16x16x32_bf16 v[94:97], v[214:217], v[190:193], v[94:97]
	v_mfma_f32_16x16x32_bf16 v[90:93], v[222:225], v[190:193], v[90:93]
	v_mfma_f32_16x16x32_bf16 v[78:81], v[214:217], v[198:201], v[78:81]
	v_mfma_f32_16x16x32_bf16 v[74:77], v[222:225], v[198:201], v[74:77]
	v_mfma_f32_16x16x32_bf16 v[70:73], v[214:217], v[206:209], v[70:73]
	v_mfma_f32_16x16x32_bf16 v[66:69], v[222:225], v[206:209], v[66:69]
	v_mfma_f32_16x16x32_bf16 v[110:113], v[218:221], v[186:189], v[110:113]
	v_mfma_f32_16x16x32_bf16 v[106:109], v[226:229], v[186:189], v[106:109]
	v_mfma_f32_16x16x32_bf16 v[94:97], v[218:221], v[194:197], v[94:97]
	v_mfma_f32_16x16x32_bf16 v[90:93], v[226:229], v[194:197], v[90:93]
	v_mfma_f32_16x16x32_bf16 v[78:81], v[218:221], v[202:205], v[78:81]
	v_mfma_f32_16x16x32_bf16 v[74:77], v[226:229], v[202:205], v[74:77]
	v_mfma_f32_16x16x32_bf16 v[70:73], v[218:221], v[210:213], v[70:73]
	v_mfma_f32_16x16x32_bf16 v[66:69], v[226:229], v[210:213], v[66:69]
	s_setprio 0
	s_mov_b32 m0, s41
	s_barrier
	ds_read_b128 v[182:185], v151 offset:16384
	ds_read_b128 v[186:189], v151 offset:17408
	ds_read_b128 v[190:193], v151 offset:18432
	ds_read_b128 v[194:197], v151 offset:19456
	ds_read_b128 v[198:201], v151 offset:20480
	ds_read_b128 v[202:205], v151 offset:21504
	ds_read_b128 v[206:209], v151 offset:22528
	ds_read_b128 v[210:213], v151 offset:23552
	global_load_lds_dwordx4 v134, s[50:51]
	s_mov_b32 m0, s55
	s_nop 0
	global_load_lds_dwordx4 v132, s[50:51]
	s_barrier
	s_waitcnt lgkmcnt(0)
	s_setprio 1
	s_waitcnt lgkmcnt(0)
	v_mfma_f32_16x16x32_bf16 v[62:65], v[158:161], v[182:185], v[62:65]
	v_mfma_f32_16x16x32_bf16 v[58:61], v[166:169], v[182:185], v[58:61]
	v_mfma_f32_16x16x32_bf16 v[54:57], v[158:161], v[190:193], v[54:57]
	v_mfma_f32_16x16x32_bf16 v[50:53], v[166:169], v[190:193], v[50:53]
	v_mfma_f32_16x16x32_bf16 v[38:41], v[158:161], v[198:201], v[38:41]
	v_mfma_f32_16x16x32_bf16 v[34:37], v[166:169], v[198:201], v[34:37]
	v_mfma_f32_16x16x32_bf16 v[22:25], v[158:161], v[206:209], v[22:25]
	v_mfma_f32_16x16x32_bf16 v[18:21], v[166:169], v[206:209], v[18:21]
	v_mfma_f32_16x16x32_bf16 v[62:65], v[162:165], v[186:189], v[62:65]
	v_mfma_f32_16x16x32_bf16 v[58:61], v[178:181], v[186:189], v[58:61]
	v_mfma_f32_16x16x32_bf16 v[54:57], v[162:165], v[194:197], v[54:57]
	v_mfma_f32_16x16x32_bf16 v[50:53], v[178:181], v[194:197], v[50:53]
	v_mfma_f32_16x16x32_bf16 v[38:41], v[162:165], v[202:205], v[38:41]
	v_mfma_f32_16x16x32_bf16 v[34:37], v[178:181], v[202:205], v[34:37]
	v_mfma_f32_16x16x32_bf16 v[22:25], v[162:165], v[210:213], v[22:25]
	v_mfma_f32_16x16x32_bf16 v[18:21], v[178:181], v[210:213], v[18:21]
	s_setprio 0
	s_barrier
	s_add_u32 s86, s6, 0x80000
	s_addc_u32 s87, s7, 0
	s_add_i32 s69, s78, s26
	s_mov_b32 m0, s69
	s_nop 0
	global_load_lds_dwordx4 v0, s[86:87]
	s_add_i32 m0, s69, 0x2000
	s_nop 0
	global_load_lds_dwordx4 v130, s[86:87]
	s_waitcnt vmcnt(6)
	s_barrier
; #define PG8_STAGE(bufoff, gbase, voff) do { _Pragma("unroll") for (int _i = 0; _i < 2; ++_i) \
;         __builtin_amdgcn_global_load_lds((const unsigned*)((const char*)(gbase) + (voff)[_i]), (LAS unsigned*)(lds + (bufoff) + ldsw + _i * 8192), 16, 0, 0); } while (0)
; #define PG8_LDA(dst, b, h) do { _Pragma("unroll") for (int m = 0; m < 4; ++m) _Pragma("unroll") for (int k = 0; k < 2; ++k) dst[m][k] = *(const LAS bf16x8*)(lds + PG8_SA(b, h) + aoff + m * 2048 + k * 1024); } while (0)
; #define PG8_LDB(dst, b, h) do { _Pragma("unroll") for (int n = 0; n < 2; ++n) _Pragma("unroll") for (int k = 0; k < 2; ++k) dst[n][k] = *(const LAS bf16x8*)(lds + PG8_SB(b, h) + boff + n * 2048 + k * 1024); } while (0)
; #define PG8_MMA(ai, bj, At, Bt) do { __builtin_amdgcn_s_setprio(1); _Pragma("unroll") for (int m = 0; m < 4; ++m) _Pragma("unroll") for (int n = 0; n < 2; ++n) _Pragma("unroll") for (int k = 0; k < 2; ++k) \
;         acc[ai][bj][m][n] = __builtin_amdgcn_mfma_f32_16x16x32_bf16(Bt[n][k], At[m][k], acc[ai][bj][m][n], 0, 0, 0); __builtin_amdgcn_s_setprio(0); } while (0)
; #define PG8_WAIT_V(n) asm volatile("s_waitcnt vmcnt(" #n ")" ::: "memory")
; #define PG8_WAIT_L(n) asm volatile("s_waitcnt lgkmcnt(" #n ")" ::: "memory")
; #define PG8_BAR __builtin_amdgcn_s_barrier()
; #define PG8_SCHED __builtin_amdgcn_sched_barrier(0)
; template <class Epi>
; DI void gemm_phase(LAS unsigned char* lds, const Gemm g, const StaticOrder& S, const Epi& E, const int tid) {
;     ...
;             PG8_WAIT_V(6); PG8_BAR; PG8_MMA(1, 1, At, B1); PG8_BAR;
;             PG8_LDB(B0, 1, 0); PG8_SCHED; PG8_LDA(At, 1, 0); PG8_STAGE(PG8_SA(0, 1), a2 + hstepA, voffA);
;             PG8_WAIT_L(8); PG8_BAR; PG8_WAIT_L(0); PG8_MMA(0, 0, At, B0); PG8_BAR; PG8_SCHED;
;             PG8_LDB(B1, 1, 1); PG8_STAGE(PG8_SB(1, 0), b3, voffB);
;             PG8_BAR; PG8_WAIT_L(0); PG8_MMA(0, 1, At, B1); PG8_BAR;
;             PG8_LDA(At, 1, 1); PG8_STAGE(PG8_SA(1, 0), a3, voffA);
;             PG8_BAR; PG8_WAIT_L(0); PG8_MMA(1, 0, At, B0); PG8_BAR; PG8_SCHED;
	s_setprio 1
	v_mfma_f32_16x16x32_bf16 v[46:49], v[214:217], v[182:185], v[46:49]
	v_mfma_f32_16x16x32_bf16 v[42:45], v[222:225], v[182:185], v[42:45]
	v_mfma_f32_16x16x32_bf16 v[30:33], v[214:217], v[190:193], v[30:33]
	v_mfma_f32_16x16x32_bf16 v[26:29], v[222:225], v[190:193], v[26:29]
	v_mfma_f32_16x16x32_bf16 v[14:17], v[214:217], v[198:201], v[14:17]
	v_mfma_f32_16x16x32_bf16 v[10:13], v[222:225], v[198:201], v[10:13]
	v_mfma_f32_16x16x32_bf16 v[6:9], v[214:217], v[206:209], v[6:9]
	v_mfma_f32_16x16x32_bf16 v[2:5], v[222:225], v[206:209], v[2:5]
	v_mfma_f32_16x16x32_bf16 v[46:49], v[218:221], v[186:189], v[46:49]
	v_mfma_f32_16x16x32_bf16 v[42:45], v[226:229], v[186:189], v[42:45]
	v_mfma_f32_16x16x32_bf16 v[30:33], v[218:221], v[194:197], v[30:33]
	v_mfma_f32_16x16x32_bf16 v[26:29], v[226:229], v[194:197], v[26:29]
	v_mfma_f32_16x16x32_bf16 v[14:17], v[218:221], v[202:205], v[14:17]
	v_mfma_f32_16x16x32_bf16 v[10:13], v[226:229], v[202:205], v[10:13]
	v_mfma_f32_16x16x32_bf16 v[6:9], v[218:221], v[210:213], v[6:9]
	v_mfma_f32_16x16x32_bf16 v[2:5], v[226:229], v[210:213], v[2:5]
	s_setprio 0
	s_add_i32 s69, 0, 0x18000
	s_barrier
	ds_read_b128 v[158:161], v243
	ds_read_b128 v[162:165], v243 offset:1024
	ds_read_b128 v[166:169], v243 offset:2048
	ds_read_b128 v[178:181], v243 offset:3072
	s_add_u32 s50, s50, 0x80000
	s_addc_u32 s51, s51, 0
	s_mov_b32 m0, s56
	s_nop 0
	ds_read_b128 v[182:185], v151 offset:32768
	ds_read_b128 v[186:189], v151 offset:33792
	ds_read_b128 v[190:193], v151 offset:34816
	ds_read_b128 v[194:197], v151 offset:35840
	ds_read_b128 v[198:201], v151 offset:36864
	ds_read_b128 v[202:205], v151 offset:37888
	ds_read_b128 v[206:209], v151 offset:38912
	ds_read_b128 v[210:213], v151 offset:39936
	global_load_lds_dwordx4 v134, s[50:51]
	s_mov_b32 m0, s57
	s_nop 0
	global_load_lds_dwordx4 v132, s[50:51]
	s_waitcnt lgkmcnt(8)
	s_barrier
	s_waitcnt lgkmcnt(0)
	s_setprio 1
	s_waitcnt lgkmcnt(0)
	v_mfma_f32_16x16x32_bf16 v[126:129], v[158:161], v[182:185], v[126:129]
	v_mfma_f32_16x16x32_bf16 v[122:125], v[166:169], v[182:185], v[122:125]
	v_mfma_f32_16x16x32_bf16 v[118:121], v[158:161], v[190:193], v[118:121]
	v_mfma_f32_16x16x32_bf16 v[114:117], v[166:169], v[190:193], v[114:117]
	v_mfma_f32_16x16x32_bf16 v[102:105], v[158:161], v[198:201], v[102:105]
	v_mfma_f32_16x16x32_bf16 v[98:101], v[166:169], v[198:201], v[98:101]
	v_mfma_f32_16x16x32_bf16 v[86:89], v[158:161], v[206:209], v[86:89]
	v_mfma_f32_16x16x32_bf16 v[82:85], v[166:169], v[206:209], v[82:85]
	v_mfma_f32_16x16x32_bf16 v[126:129], v[162:165], v[186:189], v[126:129]
	v_mfma_f32_16x16x32_bf16 v[122:125], v[178:181], v[186:189], v[122:125]
	v_mfma_f32_16x16x32_bf16 v[118:121], v[162:165], v[194:197], v[118:121]
	v_mfma_f32_16x16x32_bf16 v[114:117], v[178:181], v[194:197], v[114:117]
	v_mfma_f32_16x16x32_bf16 v[102:105], v[162:165], v[202:205], v[102:105]
	v_mfma_f32_16x16x32_bf16 v[98:101], v[178:181], v[202:205], v[98:101]
	v_mfma_f32_16x16x32_bf16 v[86:89], v[162:165], v[210:213], v[86:89]
	v_mfma_f32_16x16x32_bf16 v[82:85], v[178:181], v[210:213], v[82:85]
	s_setprio 0
	s_barrier
	s_add_i32 s50, 0, 0x1c000
	s_add_i32 s51, s69, s26
	s_add_u32 s86, s6, s84
	s_addc_u32 s87, s7, s85
	s_mov_b32 m0, s51
	ds_read_b128 v[214:217], v244
	ds_read_b128 v[218:221], v244 offset:1024
	ds_read_b128 v[222:225], v244 offset:2048
	ds_read_b128 v[226:229], v244 offset:3072
	global_load_lds_dwordx4 v0, s[86:87]
	s_add_i32 m0, s51, 0x2000
	s_nop 0
	global_load_lds_dwordx4 v130, s[86:87]
	s_barrier
	s_waitcnt lgkmcnt(0)
	s_setprio 1
	s_waitcnt lgkmcnt(0)
	v_mfma_f32_16x16x32_bf16 v[110:113], v[214:217], v[182:185], v[110:113]
	v_mfma_f32_16x16x32_bf16 v[106:109], v[222:225], v[182:185], v[106:109]
	v_mfma_f32_16x16x32_bf16 v[94:97], v[214:217], v[190:193], v[94:97]
	v_mfma_f32_16x16x32_bf16 v[90:93], v[222:225], v[190:193], v[90:93]
	v_mfma_f32_16x16x32_bf16 v[78:81], v[214:217], v[198:201], v[78:81]
	v_mfma_f32_16x16x32_bf16 v[74:77], v[222:225], v[198:201], v[74:77]
	v_mfma_f32_16x16x32_bf16 v[70:73], v[214:217], v[206:209], v[70:73]
	v_mfma_f32_16x16x32_bf16 v[66:69], v[222:225], v[206:209], v[66:69]
	v_mfma_f32_16x16x32_bf16 v[110:113], v[218:221], v[186:189], v[110:113]
	v_mfma_f32_16x16x32_bf16 v[106:109], v[226:229], v[186:189], v[106:109]
	v_mfma_f32_16x16x32_bf16 v[94:97], v[218:221], v[194:197], v[94:97]
	v_mfma_f32_16x16x32_bf16 v[90:93], v[226:229], v[194:197], v[90:93]
	v_mfma_f32_16x16x32_bf16 v[78:81], v[218:221], v[202:205], v[78:81]
	v_mfma_f32_16x16x32_bf16 v[74:77], v[226:229], v[202:205], v[74:77]
	v_mfma_f32_16x16x32_bf16 v[70:73], v[218:221], v[210:213], v[70:73]
	v_mfma_f32_16x16x32_bf16 v[66:69], v[226:229], v[210:213], v[66:69]
	s_setprio 0
	s_mov_b32 m0, s59
	s_nop 0
	s_barrier
	ds_read_b128 v[182:185], v151 offset:49152
	ds_read_b128 v[186:189], v151 offset:50176
	ds_read_b128 v[190:193], v151 offset:51200
	ds_read_b128 v[194:197], v151 offset:52224
	ds_read_b128 v[198:201], v151 offset:53248
	ds_read_b128 v[202:205], v151 offset:54272
	ds_read_b128 v[206:209], v151 offset:55296
	ds_read_b128 v[210:213], v151 offset:56320
	global_load_lds_dwordx4 v134, s[8:9]
	s_mov_b32 m0, s60
	s_nop 0
	global_load_lds_dwordx4 v132, s[8:9]
	s_barrier
; DI unsigned pk2(float a, float b) { f32x2 v = {a, b}; bf16v2 r = __builtin_convertvector(v, bf16v2); return __builtin_bit_cast(unsigned, r); }
; #define PG8_STAGE(bufoff, gbase, voff) do { _Pragma("unroll") for (int _i = 0; _i < 2; ++_i) \
;         __builtin_amdgcn_global_load_lds((const unsigned*)((const char*)(gbase) + (voff)[_i]), (LAS unsigned*)(lds + (bufoff) + ldsw + _i * 8192), 16, 0, 0); } while (0)
; #define PG8_MMA(ai, bj, At, Bt) do { __builtin_amdgcn_s_setprio(1); _Pragma("unroll") for (int m = 0; m < 4; ++m) _Pragma("unroll") for (int n = 0; n < 2; ++n) _Pragma("unroll") for (int k = 0; k < 2; ++k) \
;         acc[ai][bj][m][n] = __builtin_amdgcn_mfma_f32_16x16x32_bf16(Bt[n][k], At[m][k], acc[ai][bj][m][n], 0, 0, 0); __builtin_amdgcn_s_setprio(0); } while (0)
; #define PG8_WAIT_V(n) asm volatile("s_waitcnt vmcnt(" #n ")" ::: "memory")
; #define PG8_WAIT_L(n) asm volatile("s_waitcnt lgkmcnt(" #n ")" ::: "memory")
; #define PG8_BAR __builtin_amdgcn_s_barrier()
; #define PG8_SCHED __builtin_amdgcn_sched_barrier(0)
;     DI void operator()(const f32x4 (&acc)[2][2][4][2], const Unit& u, int wr, int wc, int fr, int fq) const {
;         if (nt) {
;             unsigned char* tb = (unsigned char*)O + ((size_t)(u.pm * nt + u.pn) << 17) + (wr * 4 + wc) * 1024 + (fq * 16 + fr) * 16;
; #pragma unroll
;             for (int ai = 0; ai < 2; ++ai)
; #pragma unroll
;                 for (int m = 0; m < 4; ++m)
; #pragma unroll
;                     for (int bj = 0; bj < 2; ++bj) { const f32x4 v0 = acc[ai][bj][m][0], v1 = acc[ai][bj][m][1];
;                         u32x4 w; w.x = pk2(v0[0], v0[1]); w.y = pk2(v0[2], v0[3]); w.z = pk2(v1[0], v1[1]); w.w = pk2(v1[2], v1[3]);
;                         *(u32x4*)(tb + ((ai * 4 + m) * 2 + bj) * 8192) = w; }
; template <class Epi>
; DI void gemm_phase(LAS unsigned char* lds, const Gemm g, const StaticOrder& S, const Epi& E, const int tid) {
;     ...
;             PG8_BAR; PG8_WAIT_L(0); PG8_MMA(1, 0, At, B0); PG8_BAR; PG8_SCHED;
;             PG8_STAGE(PG8_SB(1, 1), b3 + hstepB, voffB);
;             PG8_WAIT_V(6); PG8_BAR; PG8_MMA(1, 1, At, B1); PG8_BAR;
;         }
;         E(acc, cur, wr, wc, fr, fq);
;         if (!has_next) break;
	s_waitcnt lgkmcnt(0)
	s_setprio 1
	s_waitcnt lgkmcnt(0)
	v_mfma_f32_16x16x32_bf16 v[62:65], v[158:161], v[182:185], v[62:65]
	v_mfma_f32_16x16x32_bf16 v[58:61], v[166:169], v[182:185], v[58:61]
	v_mfma_f32_16x16x32_bf16 v[54:57], v[158:161], v[190:193], v[54:57]
	v_mfma_f32_16x16x32_bf16 v[50:53], v[166:169], v[190:193], v[50:53]
	v_mfma_f32_16x16x32_bf16 v[38:41], v[158:161], v[198:201], v[38:41]
	v_mfma_f32_16x16x32_bf16 v[34:37], v[166:169], v[198:201], v[34:37]
	v_mfma_f32_16x16x32_bf16 v[22:25], v[158:161], v[206:209], v[22:25]
	v_mfma_f32_16x16x32_bf16 v[18:21], v[166:169], v[206:209], v[18:21]
	v_mfma_f32_16x16x32_bf16 v[62:65], v[162:165], v[186:189], v[62:65]
	v_mfma_f32_16x16x32_bf16 v[58:61], v[178:181], v[186:189], v[58:61]
	v_mfma_f32_16x16x32_bf16 v[54:57], v[162:165], v[194:197], v[54:57]
	v_mfma_f32_16x16x32_bf16 v[50:53], v[178:181], v[194:197], v[50:53]
	v_mfma_f32_16x16x32_bf16 v[38:41], v[162:165], v[202:205], v[38:41]
	v_mfma_f32_16x16x32_bf16 v[34:37], v[178:181], v[202:205], v[34:37]
	v_mfma_f32_16x16x32_bf16 v[22:25], v[162:165], v[210:213], v[22:25]
	v_mfma_f32_16x16x32_bf16 v[18:21], v[178:181], v[210:213], v[18:21]
	s_setprio 0
	s_barrier
	s_add_u32 s6, s6, 0x80080
	s_addc_u32 s7, s7, 0
	s_add_i32 s8, s50, s26
	s_mov_b32 m0, s8
	s_nop 0
	global_load_lds_dwordx4 v0, s[6:7]
	s_add_i32 m0, s8, 0x2000
	s_nop 0
	global_load_lds_dwordx4 v130, s[6:7]
	s_waitcnt vmcnt(6)
	s_barrier
	s_setprio 1
	v_mfma_f32_16x16x32_bf16 v[46:49], v[214:217], v[182:185], v[46:49]
	v_mfma_f32_16x16x32_bf16 v[42:45], v[222:225], v[182:185], v[42:45]
	v_mfma_f32_16x16x32_bf16 v[30:33], v[214:217], v[190:193], v[30:33]
	v_mfma_f32_16x16x32_bf16 v[26:29], v[222:225], v[190:193], v[26:29]
	v_mfma_f32_16x16x32_bf16 v[14:17], v[214:217], v[198:201], v[14:17]
	v_mfma_f32_16x16x32_bf16 v[10:13], v[222:225], v[198:201], v[10:13]
	v_mfma_f32_16x16x32_bf16 v[6:9], v[214:217], v[206:209], v[6:9]
	v_mfma_f32_16x16x32_bf16 v[2:5], v[222:225], v[206:209], v[2:5]
	v_mfma_f32_16x16x32_bf16 v[46:49], v[218:221], v[186:189], v[46:49]
	v_mfma_f32_16x16x32_bf16 v[42:45], v[226:229], v[186:189], v[42:45]
	v_mfma_f32_16x16x32_bf16 v[30:33], v[218:221], v[194:197], v[30:33]
	v_mfma_f32_16x16x32_bf16 v[26:29], v[226:229], v[194:197], v[26:29]
	v_mfma_f32_16x16x32_bf16 v[14:17], v[218:221], v[202:205], v[14:17]
	v_mfma_f32_16x16x32_bf16 v[10:13], v[226:229], v[202:205], v[10:13]
	v_mfma_f32_16x16x32_bf16 v[6:9], v[218:221], v[210:213], v[6:9]
	v_mfma_f32_16x16x32_bf16 v[2:5], v[226:229], v[210:213], v[2:5]
	s_setprio 0
	s_add_i32 s68, s68, 2
	s_add_u32 s4, s4, 0x100
	s_addc_u32 s5, s5, 0
	s_add_u32 s6, s44, s4
	s_addc_u32 s7, s45, s5
	s_add_u32 s8, s6, 0x100
	s_addc_u32 s9, s7, 0
	s_add_u32 s69, s66, s4
	s_addc_u32 s78, s67, s5
	s_add_u32 s86, s6, 0x180
	s_addc_u32 s87, s7, 0
	s_cmpk_eq_i32 s4, 0xf00
	s_cselect_b32 s51, s30, s9
	s_cselect_b32 s50, s31, s8
	s_cselect_b32 s7, s39, s78
	s_cselect_b32 s6, s43, s69
	s_cselect_b32 s9, s65, s87
	s_cselect_b32 s8, s64, s86
	s_add_u32 s86, s44, s4
	s_addc_u32 s87, s45, s5
	s_add_u32 s86, s86, 0x80080
	s_addc_u32 s87, s87, 0
	s_cmp_gt_u32 s68, 29
	s_barrier
	s_cbranch_scc0 .LBB0_62
	s_cmpk_eq_i32 s58, 18
	s_cselect_b32 s4, 10, 24
	s_cmp_ge_u32 s63, s4
	s_cbranch_scc1 .Lepi_gate
	s_mul_i32 s4, s40, s58
	s_add_i32 s4, s4, s63
	s_ashr_i32 s5, s4, 31
	s_lshl_b64 s[4:5], s[4:5], 17
	v_lshl_add_u64 v[144:145], v[136:137], 0, s[4:5]
	s_movk_i32 s4, 0x2000
	v_cvt_pk_bf16_f32 v110, v110, v111
	v_cvt_pk_bf16_f32 v111, v112, v113
	v_cvt_pk_bf16_f32 v112, v106, v107
	v_add_co_u32_e32 v106, vcc, s4, v144
	v_cvt_pk_bf16_f32 v113, v108, v109
	s_nop 0
	v_addc_co_u32_e32 v107, vcc, 0, v145, vcc
	global_store_dwordx4 v[106:107], v[110:113], off
	s_movk_i32 s4, 0x6000
	v_cvt_pk_bf16_f32 v94, v94, v95
	v_add_co_u32_e32 v110, vcc, s3, v144
	v_cvt_pk_bf16_f32 v95, v96, v97
	s_nop 0
	v_addc_co_u32_e32 v111, vcc, 0, v145, vcc
	v_cvt_pk_bf16_f32 v96, v90, v91
	v_add_co_u32_e32 v90, vcc, s4, v144
	v_cvt_pk_bf16_f32 v97, v92, v93
	s_nop 0
	v_addc_co_u32_e32 v91, vcc, 0, v145, vcc
	s_mov_b32 s4, 0x8000
	global_store_dwordx4 v[90:91], v[94:97], off
	v_cvt_pk_bf16_f32 v78, v78, v79
	v_cvt_pk_bf16_f32 v79, v80, v81
	v_add_co_u32_e32 v94, vcc, s4, v144
	s_mov_b32 s4, 0xa000
	s_nop 0
	v_addc_co_u32_e32 v95, vcc, 0, v145, vcc
	v_cvt_pk_bf16_f32 v80, v74, v75
	v_add_co_u32_e32 v74, vcc, s4, v144
	v_cvt_pk_bf16_f32 v81, v76, v77
	s_nop 0
	v_addc_co_u32_e32 v75, vcc, 0, v145, vcc
	global_store_dwordx4 v[74:75], v[78:81], off
	s_mov_b32 s4, 0xe000
	v_cvt_pk_bf16_f32 v70, v70, v71
	v_add_co_u32_e32 v78, vcc, s13, v144
	v_cvt_pk_bf16_f32 v71, v72, v73
	s_nop 0
	v_addc_co_u32_e32 v79, vcc, 0, v145, vcc
	v_cvt_pk_bf16_f32 v72, v66, v67
	v_add_co_u32_e32 v66, vcc, s4, v144
	s_mov_b32 s4, 0x10000
	s_nop 0
	v_addc_co_u32_e32 v67, vcc, 0, v145, vcc
	v_cvt_pk_bf16_f32 v62, v62, v63
	v_cvt_pk_bf16_f32 v63, v64, v65
	v_cvt_pk_bf16_f32 v64, v58, v59
	v_add_co_u32_e32 v58, vcc, s4, v144
	s_mov_b32 s4, 0x12000
	s_nop 0
	v_addc_co_u32_e32 v59, vcc, 0, v145, vcc
	v_cvt_pk_bf16_f32 v46, v46, v47
	v_cvt_pk_bf16_f32 v47, v48, v49
	v_cvt_pk_bf16_f32 v48, v42, v43
	v_add_co_u32_e32 v42, vcc, s4, v144
	v_cvt_pk_bf16_f32 v49, v44, v45
	s_nop 0
	v_addc_co_u32_e32 v43, vcc, 0, v145, vcc
	s_mov_b32 s4, 0x14000
	global_store_dwordx4 v[42:43], v[46:49], off
	v_cvt_pk_bf16_f32 v30, v30, v31
	v_cvt_pk_bf16_f32 v31, v32, v33
	v_add_co_u32_e32 v46, vcc, s4, v144
	s_mov_b32 s4, 0x16000
	s_nop 0
	v_addc_co_u32_e32 v47, vcc, 0, v145, vcc
	v_cvt_pk_bf16_f32 v32, v26, v27
	v_add_co_u32_e32 v26, vcc, s4, v144
	v_cvt_pk_bf16_f32 v33, v28, v29
	s_nop 0
	v_addc_co_u32_e32 v27, vcc, 0, v145, vcc
; DI unsigned pk2(float a, float b) { f32x2 v = {a, b}; bf16v2 r = __builtin_convertvector(v, bf16v2); return __builtin_bit_cast(unsigned, r); }
;     DI void operator()(const f32x4 (&acc)[2][2][4][2], const Unit& u, int wr, int wc, int fr, int fq) const {
;     ...
;             unsigned char* tb = (unsigned char*)O + ((size_t)(u.pm * nt + u.pn) << 17) + (wr * 4 + wc) * 1024 + (fq * 16 + fr) * 16;
; #pragma unroll
;             for (int ai = 0; ai < 2; ++ai)
; #pragma unroll
;                 for (int m = 0; m < 4; ++m)
; #pragma unroll
;                     for (int bj = 0; bj < 2; ++bj) { const f32x4 v0 = acc[ai][bj][m][0], v1 = acc[ai][bj][m][1];
;                         u32x4 w; w.x = pk2(v0[0], v0[1]); w.y = pk2(v0[2], v0[3]); w.z = pk2(v1[0], v1[1]); w.w = pk2(v1[2], v1[3]);
;                         *(u32x4*)(tb + ((ai * 4 + m) * 2 + bj) * 8192) = w; }
; template <class Epi>
; DI void gemm_phase(LAS unsigned char* lds, const Gemm g, const StaticOrder& S, const Epi& E, const int tid) {
;     ...
;         if (!has_next) break;
; #pragma unroll
;         for (int a = 0; a < 2; ++a)
; #pragma unroll
;             for (int b = 0; b < 2; ++b)
; #pragma unroll
;                 for (int m = 0; m < 4; ++m)
; #pragma unroll
;                     for (int n = 0; n < 2; ++n) acc[a][b][m][n] = (f32x4){0.f, 0.f, 0.f, 0.f};
;         cur = nxt; cA = nA; cB = nB; ++ui;
	s_mov_b32 s4, 0x18000
	global_store_dwordx4 v[26:27], v[30:33], off
	v_cvt_pk_bf16_f32 v14, v14, v15
	v_cvt_pk_bf16_f32 v15, v16, v17
	v_add_co_u32_e32 v30, vcc, s4, v144
	s_mov_b32 s4, 0x1a000
	s_nop 0
	v_addc_co_u32_e32 v31, vcc, 0, v145, vcc
	v_cvt_pk_bf16_f32 v16, v10, v11
	v_add_co_u32_e32 v10, vcc, s4, v144
	v_cvt_pk_bf16_f32 v17, v12, v13
	s_nop 0
	v_addc_co_u32_e32 v11, vcc, 0, v145, vcc
	s_mov_b32 s4, 0x1c000
	global_store_dwordx4 v[10:11], v[14:17], off
	v_cvt_pk_bf16_f32 v6, v6, v7
	v_cvt_pk_bf16_f32 v7, v8, v9
	v_add_co_u32_e32 v14, vcc, s4, v144
	v_cvt_pk_bf16_f32 v8, v2, v3
	s_nop 0
	v_addc_co_u32_e32 v15, vcc, 0, v145, vcc
	v_add_co_u32_e32 v2, vcc, 0x1e000, v144
	v_cvt_pk_bf16_f32 v126, v126, v127
	s_nop 0
	v_addc_co_u32_e32 v3, vcc, 0, v145, vcc
	v_cvt_pk_bf16_f32 v127, v128, v129
	v_cvt_pk_bf16_f32 v128, v122, v123
	v_cvt_pk_bf16_f32 v129, v124, v125
	v_cvt_pk_bf16_f32 v106, v118, v119
	v_cvt_pk_bf16_f32 v107, v120, v121
	v_cvt_pk_bf16_f32 v108, v114, v115
	v_cvt_pk_bf16_f32 v109, v116, v117
	v_cvt_pk_bf16_f32 v90, v102, v103
	v_cvt_pk_bf16_f32 v91, v104, v105
	v_cvt_pk_bf16_f32 v92, v98, v99
	v_cvt_pk_bf16_f32 v93, v100, v101
	v_cvt_pk_bf16_f32 v74, v86, v87
	v_cvt_pk_bf16_f32 v75, v88, v89
	v_cvt_pk_bf16_f32 v76, v82, v83
	v_cvt_pk_bf16_f32 v77, v84, v85
	v_cvt_pk_bf16_f32 v73, v68, v69
	v_cvt_pk_bf16_f32 v65, v60, v61
	v_cvt_pk_bf16_f32 v42, v54, v55
	v_cvt_pk_bf16_f32 v43, v56, v57
	v_cvt_pk_bf16_f32 v44, v50, v51
	v_cvt_pk_bf16_f32 v45, v52, v53
	v_cvt_pk_bf16_f32 v26, v38, v39
	v_cvt_pk_bf16_f32 v27, v40, v41
	v_cvt_pk_bf16_f32 v28, v34, v35
	v_cvt_pk_bf16_f32 v29, v36, v37
	v_cvt_pk_bf16_f32 v10, v22, v23
	v_cvt_pk_bf16_f32 v11, v24, v25
	v_cvt_pk_bf16_f32 v12, v18, v19
	v_cvt_pk_bf16_f32 v13, v20, v21
	v_cvt_pk_bf16_f32 v9, v4, v5
	s_and_b64 vcc, exec, s[34:35]
	s_mov_b32 s63, s38
	s_mov_b32 s40, s42
	s_mov_b64 s[4:5], s[48:49]
	s_mov_b64 s[44:45], s[46:47]
	global_store_dwordx4 v[144:145], v[126:129], off
	global_store_dwordx4 v[110:111], v[106:109], off
	global_store_dwordx4 v[94:95], v[90:93], off
	global_store_dwordx4 v[78:79], v[74:77], off
	global_store_dwordx4 v[66:67], v[70:73], off
	global_store_dwordx4 v[58:59], v[62:65], off
	global_store_dwordx4 v[46:47], v[42:45], off
	global_store_dwordx4 v[30:31], v[26:29], off
	global_store_dwordx4 v[14:15], v[10:13], off
	global_store_dwordx4 v[2:3], v[6:9], off
	s_cbranch_vccz .LBB0_59
	s_branch .Lepi_done
; DI unsigned pk2(float a, float b) { f32x2 v = {a, b}; bf16v2 r = __builtin_convertvector(v, bf16v2); return __builtin_bit_cast(unsigned, r); }
; #define PG8_WAIT_V(n) asm volatile("s_waitcnt vmcnt(" #n ")" ::: "memory")
; #define PG8_BAR __builtin_amdgcn_s_barrier()
;     DI void operator()(const f32x4 (&acc)[2][2][4][2], const Unit& u, int wr, int wc, int fr, int fq) const {
;     ...
;             unsigned char* tb = (unsigned char*)O + ((size_t)(u.pm * nt + u.pn) << 17) + (wr * 4 + wc) * 1024 + (fq * 16 + fr) * 16;
; #pragma unroll
;             for (int ai = 0; ai < 2; ++ai)
; #pragma unroll
;                 for (int m = 0; m < 4; ++m)
; #pragma unroll
;                     for (int bj = 0; bj < 2; ++bj) { const f32x4 v0 = acc[ai][bj][m][0], v1 = acc[ai][bj][m][1];
;                         u32x4 w; w.x = pk2(v0[0], v0[1]); w.y = pk2(v0[2], v0[3]); w.z = pk2(v1[0], v1[1]); w.w = pk2(v1[2], v1[3]);
;                         *(u32x4*)(tb + ((ai * 4 + m) * 2 + bj) * 8192) = w; }
; template <class Epi>
; DI void gemm_phase(LAS unsigned char* lds, const Gemm g, const StaticOrder& S, const Epi& E, const int tid) {
;     ...
;     PG8_WAIT_V(0);
;     if (wr == 0) PG8_BAR;
;     PG8_BAR;
.Lepi_gate:
	s_mul_i32 s4, s40, s58
	s_add_i32 s4, s4, s63
	s_ashr_i32 s5, s4, 31
	s_lshl_b64 s[4:5], s[4:5], 17
	v_lshl_add_u64 v[144:145], v[136:137], 0, s[4:5]
	s_movk_i32 s4, 0x2000
	v_cvt_pk_bf16_f32 v110, v110, v111
	v_cvt_pk_bf16_f32 v111, v112, v113
	v_cvt_pk_bf16_f32 v112, v106, v107
	v_add_co_u32_e32 v106, vcc, s4, v144
	v_cvt_pk_bf16_f32 v113, v108, v109
	s_nop 0
	v_addc_co_u32_e32 v107, vcc, 0, v145, vcc
	global_store_dwordx4 v[106:107], v[110:113], off nt
	s_movk_i32 s4, 0x6000
	v_cvt_pk_bf16_f32 v94, v94, v95
	v_add_co_u32_e32 v110, vcc, s3, v144
	v_cvt_pk_bf16_f32 v95, v96, v97
	s_nop 0
	v_addc_co_u32_e32 v111, vcc, 0, v145, vcc
	v_cvt_pk_bf16_f32 v96, v90, v91
	v_add_co_u32_e32 v90, vcc, s4, v144
	v_cvt_pk_bf16_f32 v97, v92, v93
	s_nop 0
	v_addc_co_u32_e32 v91, vcc, 0, v145, vcc
	s_mov_b32 s4, 0x8000
	global_store_dwordx4 v[90:91], v[94:97], off nt
	v_cvt_pk_bf16_f32 v78, v78, v79
	v_cvt_pk_bf16_f32 v79, v80, v81
	v_add_co_u32_e32 v94, vcc, s4, v144
	s_mov_b32 s4, 0xa000
	s_nop 0
	v_addc_co_u32_e32 v95, vcc, 0, v145, vcc
	v_cvt_pk_bf16_f32 v80, v74, v75
	v_add_co_u32_e32 v74, vcc, s4, v144
	v_cvt_pk_bf16_f32 v81, v76, v77
	s_nop 0
	v_addc_co_u32_e32 v75, vcc, 0, v145, vcc
	global_store_dwordx4 v[74:75], v[78:81], off nt
	s_mov_b32 s4, 0xe000
	v_cvt_pk_bf16_f32 v70, v70, v71
	v_add_co_u32_e32 v78, vcc, s13, v144
	v_cvt_pk_bf16_f32 v71, v72, v73
	s_nop 0
	v_addc_co_u32_e32 v79, vcc, 0, v145, vcc
	v_cvt_pk_bf16_f32 v72, v66, v67
	v_add_co_u32_e32 v66, vcc, s4, v144
	s_mov_b32 s4, 0x10000
	s_nop 0
	v_addc_co_u32_e32 v67, vcc, 0, v145, vcc
	v_cvt_pk_bf16_f32 v62, v62, v63
	v_cvt_pk_bf16_f32 v63, v64, v65
	v_cvt_pk_bf16_f32 v64, v58, v59
	v_add_co_u32_e32 v58, vcc, s4, v144
	s_mov_b32 s4, 0x12000
	s_nop 0
	v_addc_co_u32_e32 v59, vcc, 0, v145, vcc
	v_cvt_pk_bf16_f32 v46, v46, v47
	v_cvt_pk_bf16_f32 v47, v48, v49
	v_cvt_pk_bf16_f32 v48, v42, v43
	v_add_co_u32_e32 v42, vcc, s4, v144
	v_cvt_pk_bf16_f32 v49, v44, v45
	s_nop 0
	v_addc_co_u32_e32 v43, vcc, 0, v145, vcc
	s_mov_b32 s4, 0x14000
	global_store_dwordx4 v[42:43], v[46:49], off nt
	v_cvt_pk_bf16_f32 v30, v30, v31
	v_cvt_pk_bf16_f32 v31, v32, v33
	v_add_co_u32_e32 v46, vcc, s4, v144
	s_mov_b32 s4, 0x16000
	s_nop 0
	v_addc_co_u32_e32 v47, vcc, 0, v145, vcc
	v_cvt_pk_bf16_f32 v32, v26, v27
	v_add_co_u32_e32 v26, vcc, s4, v144
	v_cvt_pk_bf16_f32 v33, v28, v29
	s_nop 0
	v_addc_co_u32_e32 v27, vcc, 0, v145, vcc
	s_mov_b32 s4, 0x18000
	global_store_dwordx4 v[26:27], v[30:33], off nt
	v_cvt_pk_bf16_f32 v14, v14, v15
	v_cvt_pk_bf16_f32 v15, v16, v17
	v_add_co_u32_e32 v30, vcc, s4, v144
	s_mov_b32 s4, 0x1a000
	s_nop 0
	v_addc_co_u32_e32 v31, vcc, 0, v145, vcc
	v_cvt_pk_bf16_f32 v16, v10, v11
	v_add_co_u32_e32 v10, vcc, s4, v144
	v_cvt_pk_bf16_f32 v17, v12, v13
	s_nop 0
	v_addc_co_u32_e32 v11, vcc, 0, v145, vcc
	s_mov_b32 s4, 0x1c000
	global_store_dwordx4 v[10:11], v[14:17], off nt
	v_cvt_pk_bf16_f32 v6, v6, v7
	v_cvt_pk_bf16_f32 v7, v8, v9
	v_add_co_u32_e32 v14, vcc, s4, v144
	v_cvt_pk_bf16_f32 v8, v2, v3
	s_nop 0
	v_addc_co_u32_e32 v15, vcc, 0, v145, vcc
	v_add_co_u32_e32 v2, vcc, 0x1e000, v144
	v_cvt_pk_bf16_f32 v126, v126, v127
	s_nop 0
	v_addc_co_u32_e32 v3, vcc, 0, v145, vcc
	v_cvt_pk_bf16_f32 v127, v128, v129
	v_cvt_pk_bf16_f32 v128, v122, v123
	v_cvt_pk_bf16_f32 v129, v124, v125
	v_cvt_pk_bf16_f32 v106, v118, v119
	v_cvt_pk_bf16_f32 v107, v120, v121
	v_cvt_pk_bf16_f32 v108, v114, v115
	v_cvt_pk_bf16_f32 v109, v116, v117
	v_cvt_pk_bf16_f32 v90, v102, v103
	v_cvt_pk_bf16_f32 v91, v104, v105
	v_cvt_pk_bf16_f32 v92, v98, v99
	v_cvt_pk_bf16_f32 v93, v100, v101
	v_cvt_pk_bf16_f32 v74, v86, v87
	v_cvt_pk_bf16_f32 v75, v88, v89
	v_cvt_pk_bf16_f32 v76, v82, v83
	v_cvt_pk_bf16_f32 v77, v84, v85
	v_cvt_pk_bf16_f32 v73, v68, v69
	v_cvt_pk_bf16_f32 v65, v60, v61
	v_cvt_pk_bf16_f32 v42, v54, v55
	v_cvt_pk_bf16_f32 v43, v56, v57
	v_cvt_pk_bf16_f32 v44, v50, v51
	v_cvt_pk_bf16_f32 v45, v52, v53
	v_cvt_pk_bf16_f32 v26, v38, v39
	v_cvt_pk_bf16_f32 v27, v40, v41
	v_cvt_pk_bf16_f32 v28, v34, v35
	v_cvt_pk_bf16_f32 v29, v36, v37
	v_cvt_pk_bf16_f32 v10, v22, v23
	v_cvt_pk_bf16_f32 v11, v24, v25
	v_cvt_pk_bf16_f32 v12, v18, v19
	v_cvt_pk_bf16_f32 v13, v20, v21
	v_cvt_pk_bf16_f32 v9, v4, v5
	s_and_b64 vcc, exec, s[34:35]
	s_mov_b32 s63, s38
	s_mov_b32 s40, s42
	s_mov_b64 s[4:5], s[48:49]
	s_mov_b64 s[44:45], s[46:47]
	global_store_dwordx4 v[144:145], v[126:129], off nt
	global_store_dwordx4 v[110:111], v[106:109], off nt
	global_store_dwordx4 v[94:95], v[90:93], off nt
	global_store_dwordx4 v[78:79], v[74:77], off nt
	global_store_dwordx4 v[66:67], v[70:73], off nt
	global_store_dwordx4 v[58:59], v[62:65], off nt
	global_store_dwordx4 v[46:47], v[42:45], off nt
	global_store_dwordx4 v[30:31], v[26:29], off nt
	global_store_dwordx4 v[14:15], v[10:13], off nt
	global_store_dwordx4 v[2:3], v[6:9], off nt
	s_cbranch_vccz .LBB0_59
.Lepi_done:
	s_waitcnt vmcnt(0)
	s_cmpk_gt_u32 s25, 0xff
	s_cbranch_scc1 .LBB0_66
	s_barrier
